# early acquire-inv in grid barrier + prompt attention K/V staging loads issued together + spatial bias loads hoisted
# baseline (speedup 1.0000x reference)
.LBB0_684:
	s_bfe_u32 s45, s15, 0x60001
	s_lshl_b32 s26, s15, 6
	s_lshl_b32 s46, s45, 7
	s_and_b32 s30, s26, 0xffffe000
	s_or_b32 s48, s46, s30
	s_and_b32 s44, s4, 0xffffe000
	s_and_b32 s47, s15, 1
	s_add_i32 s49, s48, 0xffffff80
	s_cmp_eq_u32 s45, 0
	s_cselect_b64 s[26:27], -1, 0
	v_mov_b32_e32 v10, s49
	v_mov_b32_e32 v11, s30
	s_and_b64 vcc, s[36:37], s[26:27]
	v_cndmask_b32_e32 v0, v10, v11, vcc
	v_add_u32_e32 v0, v0, v111
	v_ashrrev_i32_e32 v1, 31, v0
	v_lshlrev_b64 v[0:1], 9, v[0:1]
	v_lshl_add_u64 v[0:1], s[10:11], 0, v[0:1]
	s_lshl_b32 s30, s47, 7
	v_lshl_add_u64 v[0:1], v[0:1], 0, s[30:31]
	v_lshl_add_u64 v[4:5], v[0:1], 0, v[144:145]
	flat_load_dwordx4 v[16:19], v[4:5]
	s_nop 0
	flat_load_dwordx4 v[20:23], v[4:5] offset:256
	s_and_b64 vcc, s[38:39], s[26:27]
	v_cndmask_b32_e32 v8, v10, v11, vcc
	v_add_u32_e32 v8, v8, v134
	v_ashrrev_i32_e32 v9, 31, v8
	v_lshlrev_b64 v[8:9], 9, v[8:9]
	v_lshl_add_u64 v[8:9], s[10:11], 0, v[8:9]
	v_add_u32_e32 v12, v118, v125
	v_lshl_add_u64 v[8:9], v[8:9], 0, s[30:31]
	v_lshl_add_u64 v[8:9], v[8:9], 0, v[144:145]
	s_and_b64 vcc, s[40:41], s[26:27]
	v_or_b32_e32 v126, s48, v109
	v_ashrrev_i32_e32 v127, 31, v126
	v_readlane_b32 s2, v254, 19
	v_mov_b32_e32 v161, v139
	v_mov_b32_e32 v162, v138
	v_mov_b32_e32 v128, v137
	flat_load_dwordx4 v[24:27], v[8:9]
	flat_load_dwordx4 v[28:31], v[8:9] offset:256
	v_cndmask_b32_e32 v8, v10, v11, vcc
	v_add_u32_e32 v8, v8, v135
	v_ashrrev_i32_e32 v9, 31, v8
	v_lshlrev_b64 v[8:9], 9, v[8:9]
	v_lshl_add_u64 v[8:9], s[10:11], 0, v[8:9]
	v_add_u32_e32 v12, v120, v125
	v_lshl_add_u64 v[8:9], v[8:9], 0, s[30:31]
	v_lshl_add_u64 v[8:9], v[8:9], 0, v[144:145]
	s_and_b64 vcc, s[42:43], s[26:27]
	s_lshl_b32 s26, s47, 3
	s_add_i32 s26, s26, s2
	s_lshl_b32 s27, s26, 2
	flat_load_dwordx4 v[32:35], v[8:9]
	flat_load_dwordx4 v[36:39], v[8:9] offset:256
	v_cndmask_b32_e32 v8, v10, v11, vcc
	v_add_u32_e32 v8, v8, v136
	v_ashrrev_i32_e32 v9, 31, v8
	v_lshlrev_b64 v[8:9], 9, v[8:9]
	v_lshl_add_u64 v[8:9], s[10:11], 0, v[8:9]
	v_add_u32_e32 v12, v122, v125
	v_lshl_add_u64 v[8:9], v[8:9], 0, s[30:31]
	v_lshl_add_u64 v[8:9], v[8:9], 0, v[144:145]
	s_lshl_b32 s30, s26, 7
	v_add_u32_e32 v10, v124, v125
	v_mov_b32_e32 v11, s27
	s_add_i32 s26, s26, 1
	s_cmp_lg_u32 s45, 0
	v_lshl_add_u64 v[130:131], v[114:115], 0, s[30:31]
	v_lshl_add_u64 v[132:133], v[116:117], 0, s[30:31]
	flat_load_dwordx4 v[40:43], v[8:9]
	flat_load_dwordx4 v[44:47], v[8:9] offset:256
	v_lshlrev_b64 v[8:9], 11, v[126:127]
	v_lshl_add_u64 v[8:9], s[8:9], 0, v[8:9]
	v_lshl_add_u64 v[8:9], v[8:9], 0, s[30:31]
	v_lshl_add_u64 v[8:9], v[112:113], 1, v[8:9]
	global_load_dword v127, v11, s[12:13] offset:-128
	global_load_dwordx4 v[0:3], v[8:9], off
	global_load_dwordx4 v[104:107], v[8:9], off offset:32
	global_load_dwordx4 v[100:103], v[8:9], off offset:64
	global_load_dwordx4 v[96:99], v[8:9], off offset:96
	s_waitcnt vmcnt(0) lgkmcnt(0)
	v_add_u32_e32 v12, v118, v125
	ds_write_b128 v12, v[16:19]
	ds_write_b128 v140, v[20:23] offset:36864
	v_add_u32_e32 v12, v120, v125
	ds_write_b128 v12, v[24:27]
	ds_write_b128 v141, v[28:31] offset:36864
	v_add_u32_e32 v12, v122, v125
	ds_write_b128 v12, v[32:35]
	ds_write_b128 v142, v[36:39] offset:36864
	ds_write_b128 v10, v[40:43]
	ds_write_b128 v143, v[44:47] offset:36864
	s_waitcnt lgkmcnt(0)
	s_barrier
	v_cvt_f32_u32_e32 v4, s26
	v_or_b32_e32 v5, s44, v109
	v_or_b32_e32 v160, s46, v5
	s_mov_b32 s26, 0
	v_mul_f32_e32 v4, -0.5, v4
	v_exp_f32_e32 v129, v4
	s_cselect_b64 s[46:47], -1, 0

.LBB0_704:
	s_waitcnt lgkmcnt(0)
	s_barrier
	ds_read_b64_tr_b16 v[36:37], v161
	ds_read_b64_tr_b16 v[38:39], v161 offset:2304
	ds_read_b64_tr_b16 v[32:33], v161 offset:8
	ds_read_b64_tr_b16 v[34:35], v161 offset:2312
	s_waitcnt lgkmcnt(0)
	ds_read_b128 v[40:43], v177
	ds_read_b128 v[48:51], v177 offset:13056
	s_waitcnt lgkmcnt(1)
	v_mfma_f32_16x16x32_bf16 v[92:95], v[36:39], v[40:43], 0
	ds_read_b128 v[56:59], v177 offset:17408
	ds_read_b128 v[64:67], v177 offset:21760
	s_lshl_b32 s5, s44, 7
	v_mfma_f32_16x16x32_bf16 v[88:91], v[32:35], v[40:43], 0
	ds_read_b128 v[40:43], v177 offset:4352
	v_or_b32_e32 v144, s5, v183
	v_lshlrev_b32_e32 v144, 2, v144
	global_load_dword v196, v144, s[16:17]
	v_or_b32_e32 v212, s5, v182
	v_lshlrev_b32_e32 v212, 2, v212
	global_load_dword v198, v212, s[16:17]
	v_or_b32_e32 v212, s5, v181
	v_lshlrev_b32_e32 v212, 2, v212
	global_load_dword v200, v212, s[16:17]
	v_or_b32_e32 v212, s5, v180
	v_lshlrev_b32_e32 v212, 2, v212
	global_load_dword v202, v212, s[16:17]
	v_or_b32_e32 v212, s5, v179
	v_lshlrev_b32_e32 v212, 2, v212
	global_load_dword v204, v212, s[16:17]
	v_or_b32_e32 v212, s5, v178
	v_lshlrev_b32_e32 v212, 2, v212
	global_load_dword v206, v212, s[16:17]
	v_or_b32_e32 v212, s5, v113
	v_lshlrev_b32_e32 v212, 2, v212
	global_load_dword v208, v212, s[16:17]
	v_or_b32_e32 v212, s5, v111
	v_lshlrev_b32_e32 v212, 2, v212
	global_load_dword v210, v212, s[16:17]
	s_waitcnt lgkmcnt(0)
	v_mfma_f32_16x16x32_bf16 v[84:87], v[36:39], v[40:43], 0
	s_lshl_b32 s30, s4, 1
	v_lshl_add_u64 v[116:117], v[98:99], 0, s[30:31]
	s_add_i32 s27, s27, s74
	v_mfma_f32_16x16x32_bf16 v[80:83], v[32:35], v[40:43], 0
	ds_read_b128 v[40:43], v177 offset:8704
	s_cmpk_gt_i32 s27, 0x43f
	v_mfma_f32_16x16x32_bf16 v[146:149], v[36:39], v[64:67], 0
	v_mfma_f32_16x16x32_bf16 v[150:153], v[32:35], v[64:67], 0
	ds_read_b128 v[64:67], v177 offset:26112
	s_waitcnt lgkmcnt(0)
	v_mfma_f32_16x16x32_bf16 v[154:157], v[36:39], v[64:67], 0
	v_mfma_f32_16x16x32_bf16 v[184:187], v[32:35], v[64:67], 0
	ds_read_b128 v[64:67], v177 offset:30464
	ds_read_b64_tr_b16 v[192:193], v162
	ds_read_b64_tr_b16 v[194:195], v162 offset:2304
	ds_read_b64_tr_b16 v[188:189], v162 offset:8
	ds_read_b64_tr_b16 v[190:191], v162 offset:2312
	s_waitcnt lgkmcnt(0)
	v_mfma_f32_16x16x32_bf16 v[44:47], v[36:39], v[40:43], 0
	v_mfma_f32_16x16x32_bf16 v[40:43], v[32:35], v[40:43], 0
	v_mfma_f32_16x16x32_bf16 v[52:55], v[36:39], v[48:51], 0
	v_mfma_f32_16x16x32_bf16 v[48:51], v[32:35], v[48:51], 0
	v_mfma_f32_16x16x32_bf16 v[60:63], v[36:39], v[56:59], 0
	v_mfma_f32_16x16x32_bf16 v[56:59], v[32:35], v[56:59], 0
	s_waitcnt lgkmcnt(0)
	v_mfma_f32_16x16x32_bf16 v[36:39], v[36:39], v[64:67], 0
	v_mfma_f32_16x16x32_bf16 v[32:35], v[32:35], v[64:67], 0
	ds_read_b128 v[64:67], v177 offset:8768
	s_waitcnt lgkmcnt(0)
	v_mfma_f32_16x16x32_bf16 v[72:75], v[188:191], v[64:67], v[40:43]
	s_nop 2
	ds_read_b128 v[40:43], v177 offset:13120
	v_mfma_f32_16x16x32_bf16 v[76:79], v[192:195], v[64:67], v[44:47]
	s_waitcnt lgkmcnt(0)
	v_mfma_f32_16x16x32_bf16 v[68:71], v[192:195], v[40:43], v[52:55]
	v_mfma_f32_16x16x32_bf16 v[64:67], v[188:191], v[40:43], v[48:51]
	ds_read_b128 v[40:43], v177 offset:17472
	s_nop 1
	ds_read_b128 v[48:51], v177 offset:21824
	s_waitcnt lgkmcnt(1)
	v_mfma_f32_16x16x32_bf16 v[44:47], v[192:195], v[40:43], v[60:63]
	v_mfma_f32_16x16x32_bf16 v[40:43], v[188:191], v[40:43], v[56:59]
	s_nop 2
	ds_read_b128 v[56:59], v177 offset:26176
	s_waitcnt lgkmcnt(1)
	v_mfma_f32_16x16x32_bf16 v[52:55], v[192:195], v[48:51], v[146:149]
	v_mfma_f32_16x16x32_bf16 v[48:51], v[188:191], v[48:51], v[150:153]
	s_waitcnt lgkmcnt(0)
	v_mfma_f32_16x16x32_bf16 v[146:149], v[192:195], v[56:59], v[154:157]
	v_mfma_f32_16x16x32_bf16 v[150:153], v[188:191], v[56:59], v[184:187]
	ds_read_b128 v[56:59], v177 offset:30528
	ds_read_b64_tr_b16 v[184:185], v163
	ds_read_b64_tr_b16 v[186:187], v163 offset:2304
	ds_read_b64_tr_b16 v[154:155], v163 offset:8
	ds_read_b64_tr_b16 v[156:157], v163 offset:2312
	s_waitcnt lgkmcnt(0)
	s_waitcnt lgkmcnt(0)
	v_mfma_f32_16x16x32_bf16 v[36:39], v[192:195], v[56:59], v[36:39]
	v_mfma_f32_16x16x32_bf16 v[32:35], v[188:191], v[56:59], v[32:35]
	ds_read_b128 v[56:59], v177 offset:17536
	s_waitcnt lgkmcnt(0)
	v_mfma_f32_16x16x32_bf16 v[60:63], v[184:187], v[56:59], v[44:47]
	v_mfma_f32_16x16x32_bf16 v[56:59], v[154:157], v[56:59], v[40:43]
	s_nop 2
	ds_read_b128 v[40:43], v177 offset:21888
	s_waitcnt lgkmcnt(0)
	v_mfma_f32_16x16x32_bf16 v[52:55], v[184:187], v[40:43], v[52:55]
	v_mfma_f32_16x16x32_bf16 v[48:51], v[154:157], v[40:43], v[48:51]
	ds_read_b128 v[40:43], v177 offset:26240
	s_waitcnt lgkmcnt(0)
	v_mfma_f32_16x16x32_bf16 v[44:47], v[184:187], v[40:43], v[146:149]
	s_nop 2
	ds_read_b128 v[146:149], v177 offset:30592
	v_mfma_f32_16x16x32_bf16 v[40:43], v[154:157], v[40:43], v[150:153]
	s_waitcnt lgkmcnt(0)
	v_mfma_f32_16x16x32_bf16 v[36:39], v[184:187], v[146:149], v[36:39]
	v_mfma_f32_16x16x32_bf16 v[32:35], v[154:157], v[146:149], v[32:35]
	ds_read_b64_tr_b16 v[150:151], v164
	ds_read_b64_tr_b16 v[152:153], v164 offset:2304
	ds_read_b64_tr_b16 v[146:147], v164 offset:8
	ds_read_b64_tr_b16 v[148:149], v164 offset:2312
	s_waitcnt lgkmcnt(0)
	ds_read_b128 v[154:157], v177 offset:26304
	s_waitcnt lgkmcnt(0)
	v_mfma_f32_16x16x32_bf16 v[44:47], v[150:153], v[154:157], v[44:47]
	s_waitcnt vmcnt(0)
	v_pk_add_f32 v[92:93], v[92:93], v[196:197] op_sel_hi:[1,0]
	v_mfma_f32_16x16x32_bf16 v[40:43], v[146:149], v[154:157], v[40:43]
	ds_read_b128 v[154:157], v177 offset:30656
	v_pk_add_f32 v[94:95], v[94:95], v[196:197] op_sel_hi:[1,0]
	v_pk_add_f32 v[88:89], v[88:89], v[196:197] op_sel_hi:[1,0]
	s_waitcnt lgkmcnt(0)
	v_mfma_f32_16x16x32_bf16 v[32:35], v[146:149], v[154:157], v[32:35]
	v_lshlrev_b32_e32 v146, 16, v28
	v_and_b32_e32 v147, 0xffff0000, v28
	v_pk_mul_f32 v[92:93], v[92:93], v[146:147]
	v_pk_add_f32 v[90:91], v[90:91], v[196:197] op_sel_hi:[1,0]
	v_cvt_pk_bf16_f32 v28, v92, v93
	v_lshlrev_b32_e32 v92, 16, v29
	v_and_b32_e32 v93, 0xffff0000, v29
	v_pk_mul_f32 v[92:93], v[94:95], v[92:93]
	v_mfma_f32_16x16x32_bf16 v[36:39], v[150:153], v[154:157], v[36:39]
	v_cvt_pk_bf16_f32 v29, v92, v93
	v_lshlrev_b32_e32 v92, 16, v30
	v_and_b32_e32 v93, 0xffff0000, v30
	v_pk_mul_f32 v[88:89], v[88:89], v[92:93]
	s_nop 0
	v_cvt_pk_bf16_f32 v30, v88, v89
	v_lshlrev_b32_e32 v88, 16, v31
	v_and_b32_e32 v89, 0xffff0000, v31
	v_pk_mul_f32 v[88:89], v[90:91], v[88:89]
	s_nop 0
	v_cvt_pk_bf16_f32 v31, v88, v89
	v_lshlrev_b64 v[88:89], 12, v[114:115]
	v_lshl_add_u64 v[88:89], v[116:117], 0, v[88:89]
	global_store_dwordx4 v[88:89], v[28:31], off
	v_lshlrev_b32_e32 v88, 16, v24
	v_and_b32_e32 v89, 0xffff0000, v24
	v_or_b32_e32 v29, s5, v182
	v_lshlrev_b32_e32 v29, 2, v29
	v_or_b32_e32 v28, s43, v122
	v_ashrrev_i32_e32 v29, 31, v28
	v_lshlrev_b64 v[28:29], 12, v[28:29]
	v_lshl_add_u64 v[28:29], v[116:117], 0, v[28:29]
	v_pk_add_f32 v[84:85], v[84:85], v[198:199] op_sel_hi:[1,0]
	s_nop 0
	v_pk_mul_f32 v[84:85], v[84:85], v[88:89]
	v_pk_add_f32 v[86:87], v[86:87], v[198:199] op_sel_hi:[1,0]
	v_cvt_pk_bf16_f32 v24, v84, v85
	v_lshlrev_b32_e32 v84, 16, v25
	v_and_b32_e32 v85, 0xffff0000, v25
	v_pk_mul_f32 v[84:85], v[86:87], v[84:85]
	v_pk_add_f32 v[80:81], v[80:81], v[198:199] op_sel_hi:[1,0]
	v_cvt_pk_bf16_f32 v25, v84, v85
	v_lshlrev_b32_e32 v84, 16, v26
	v_and_b32_e32 v85, 0xffff0000, v26
	v_pk_mul_f32 v[80:81], v[80:81], v[84:85]
	v_pk_add_f32 v[30:31], v[82:83], v[198:199] op_sel_hi:[1,0]
	v_cvt_pk_bf16_f32 v26, v80, v81
	v_lshlrev_b32_e32 v80, 16, v27
	v_and_b32_e32 v81, 0xffff0000, v27
	v_pk_mul_f32 v[30:31], v[30:31], v[80:81]
	s_nop 0
	v_cvt_pk_bf16_f32 v27, v30, v31
	global_store_dwordx4 v[28:29], v[24:27], off
	v_lshlrev_b32_e32 v28, 16, v20
	v_and_b32_e32 v29, 0xffff0000, v20
	v_or_b32_e32 v25, s5, v181
	v_lshlrev_b32_e32 v25, 2, v25
	v_or_b32_e32 v24, s43, v123
	v_ashrrev_i32_e32 v25, 31, v24
	v_lshlrev_b64 v[24:25], 12, v[24:25]
	v_lshl_add_u64 v[24:25], v[116:117], 0, v[24:25]
	v_pk_add_f32 v[30:31], v[76:77], v[200:201] op_sel_hi:[1,0]
	s_nop 0
	v_pk_mul_f32 v[28:29], v[30:31], v[28:29]
	v_pk_add_f32 v[30:31], v[78:79], v[200:201] op_sel_hi:[1,0]
	v_cvt_pk_bf16_f32 v20, v28, v29
	v_lshlrev_b32_e32 v28, 16, v21
	v_and_b32_e32 v29, 0xffff0000, v21
	v_pk_mul_f32 v[28:29], v[30:31], v[28:29]
	v_pk_add_f32 v[30:31], v[72:73], v[200:201] op_sel_hi:[1,0]
	v_cvt_pk_bf16_f32 v21, v28, v29
	v_lshlrev_b32_e32 v28, 16, v22
	v_and_b32_e32 v29, 0xffff0000, v22
	v_pk_mul_f32 v[28:29], v[30:31], v[28:29]
	v_pk_add_f32 v[26:27], v[74:75], v[200:201] op_sel_hi:[1,0]
	v_cvt_pk_bf16_f32 v22, v28, v29
	v_lshlrev_b32_e32 v28, 16, v23
	v_and_b32_e32 v29, 0xffff0000, v23
	v_pk_mul_f32 v[26:27], v[26:27], v[28:29]
	s_nop 0
	v_cvt_pk_bf16_f32 v23, v26, v27
	global_store_dwordx4 v[24:25], v[20:23], off
	v_lshlrev_b32_e32 v24, 16, v16
	v_and_b32_e32 v25, 0xffff0000, v16
	v_or_b32_e32 v21, s5, v180
	v_lshlrev_b32_e32 v21, 2, v21
	v_or_b32_e32 v20, s43, v124
	v_ashrrev_i32_e32 v21, 31, v20
	v_lshlrev_b64 v[20:21], 12, v[20:21]
	v_lshl_add_u64 v[20:21], v[116:117], 0, v[20:21]
	v_pk_add_f32 v[26:27], v[68:69], v[202:203] op_sel_hi:[1,0]
	s_nop 0
	v_pk_mul_f32 v[24:25], v[26:27], v[24:25]
	v_pk_add_f32 v[26:27], v[70:71], v[202:203] op_sel_hi:[1,0]
	v_cvt_pk_bf16_f32 v16, v24, v25
	v_lshlrev_b32_e32 v24, 16, v17
	v_and_b32_e32 v25, 0xffff0000, v17
	v_pk_mul_f32 v[24:25], v[26:27], v[24:25]
	v_pk_add_f32 v[26:27], v[64:65], v[202:203] op_sel_hi:[1,0]
	v_cvt_pk_bf16_f32 v17, v24, v25
	v_lshlrev_b32_e32 v24, 16, v18
	v_and_b32_e32 v25, 0xffff0000, v18
	v_pk_mul_f32 v[24:25], v[26:27], v[24:25]
	v_pk_add_f32 v[22:23], v[66:67], v[202:203] op_sel_hi:[1,0]
	v_cvt_pk_bf16_f32 v18, v24, v25
	v_lshlrev_b32_e32 v24, 16, v19
	v_and_b32_e32 v25, 0xffff0000, v19
	v_pk_mul_f32 v[22:23], v[22:23], v[24:25]
	s_nop 0
	v_cvt_pk_bf16_f32 v19, v22, v23
	global_store_dwordx4 v[20:21], v[16:19], off
	v_lshlrev_b32_e32 v20, 16, v12
	v_and_b32_e32 v21, 0xffff0000, v12
	v_or_b32_e32 v17, s5, v179
	v_lshlrev_b32_e32 v17, 2, v17
	v_or_b32_e32 v16, s43, v125
	v_ashrrev_i32_e32 v17, 31, v16
	v_lshlrev_b64 v[16:17], 12, v[16:17]
	v_lshl_add_u64 v[16:17], v[116:117], 0, v[16:17]
	v_pk_add_f32 v[22:23], v[60:61], v[204:205] op_sel_hi:[1,0]
	s_nop 0
	v_pk_mul_f32 v[20:21], v[22:23], v[20:21]
	v_pk_add_f32 v[22:23], v[62:63], v[204:205] op_sel_hi:[1,0]
	v_cvt_pk_bf16_f32 v12, v20, v21
	v_lshlrev_b32_e32 v20, 16, v13
	v_and_b32_e32 v21, 0xffff0000, v13
	v_pk_mul_f32 v[20:21], v[22:23], v[20:21]
	v_pk_add_f32 v[22:23], v[56:57], v[204:205] op_sel_hi:[1,0]
	v_cvt_pk_bf16_f32 v13, v20, v21
	v_lshlrev_b32_e32 v20, 16, v14
	v_and_b32_e32 v21, 0xffff0000, v14
	v_pk_mul_f32 v[20:21], v[22:23], v[20:21]
	v_pk_add_f32 v[18:19], v[58:59], v[204:205] op_sel_hi:[1,0]
	v_cvt_pk_bf16_f32 v14, v20, v21
	v_lshlrev_b32_e32 v20, 16, v15
	v_and_b32_e32 v21, 0xffff0000, v15
	v_pk_mul_f32 v[18:19], v[18:19], v[20:21]
	s_nop 0
	v_cvt_pk_bf16_f32 v15, v18, v19
	global_store_dwordx4 v[16:17], v[12:15], off
	v_lshlrev_b32_e32 v16, 16, v8
	v_and_b32_e32 v17, 0xffff0000, v8
	v_or_b32_e32 v13, s5, v178
	v_lshlrev_b32_e32 v13, 2, v13
	v_or_b32_e32 v12, s43, v126
	v_ashrrev_i32_e32 v13, 31, v12
	v_lshlrev_b64 v[12:13], 12, v[12:13]
	v_lshl_add_u64 v[12:13], v[116:117], 0, v[12:13]
	v_pk_add_f32 v[18:19], v[52:53], v[206:207] op_sel_hi:[1,0]
	s_nop 0
	v_pk_mul_f32 v[16:17], v[18:19], v[16:17]
	v_pk_add_f32 v[18:19], v[54:55], v[206:207] op_sel_hi:[1,0]
	v_cvt_pk_bf16_f32 v8, v16, v17
	v_lshlrev_b32_e32 v16, 16, v9
	v_and_b32_e32 v17, 0xffff0000, v9
	v_pk_mul_f32 v[16:17], v[18:19], v[16:17]
	v_pk_add_f32 v[18:19], v[48:49], v[206:207] op_sel_hi:[1,0]
	v_cvt_pk_bf16_f32 v9, v16, v17
	v_lshlrev_b32_e32 v16, 16, v10
	v_and_b32_e32 v17, 0xffff0000, v10
	v_pk_mul_f32 v[16:17], v[18:19], v[16:17]
	v_pk_add_f32 v[14:15], v[50:51], v[206:207] op_sel_hi:[1,0]
	v_cvt_pk_bf16_f32 v10, v16, v17
	v_lshlrev_b32_e32 v16, 16, v11
	v_and_b32_e32 v17, 0xffff0000, v11
	v_pk_mul_f32 v[14:15], v[14:15], v[16:17]
	s_nop 0
	v_cvt_pk_bf16_f32 v11, v14, v15
	global_store_dwordx4 v[12:13], v[8:11], off
	v_lshlrev_b32_e32 v12, 16, v4
	v_and_b32_e32 v13, 0xffff0000, v4
	v_or_b32_e32 v9, s5, v113
	v_lshlrev_b32_e32 v9, 2, v9
	v_or_b32_e32 v8, s43, v127
	v_ashrrev_i32_e32 v9, 31, v8
	v_lshlrev_b64 v[8:9], 12, v[8:9]
	v_lshl_add_u64 v[8:9], v[116:117], 0, v[8:9]
	v_pk_add_f32 v[14:15], v[44:45], v[208:209] op_sel_hi:[1,0]
	s_nop 0
	v_pk_mul_f32 v[12:13], v[14:15], v[12:13]
	v_pk_add_f32 v[14:15], v[46:47], v[208:209] op_sel_hi:[1,0]
	v_cvt_pk_bf16_f32 v4, v12, v13
	v_lshlrev_b32_e32 v12, 16, v5
	v_and_b32_e32 v13, 0xffff0000, v5
	v_pk_mul_f32 v[12:13], v[14:15], v[12:13]
	v_pk_add_f32 v[14:15], v[40:41], v[208:209] op_sel_hi:[1,0]
	v_cvt_pk_bf16_f32 v5, v12, v13
	v_lshlrev_b32_e32 v12, 16, v6
	v_and_b32_e32 v13, 0xffff0000, v6
	v_pk_mul_f32 v[12:13], v[14:15], v[12:13]
	v_pk_add_f32 v[10:11], v[42:43], v[208:209] op_sel_hi:[1,0]
	v_cvt_pk_bf16_f32 v6, v12, v13
	v_lshlrev_b32_e32 v12, 16, v7
	v_and_b32_e32 v13, 0xffff0000, v7
	v_pk_mul_f32 v[10:11], v[10:11], v[12:13]
	s_nop 0
	v_cvt_pk_bf16_f32 v7, v10, v11
	global_store_dwordx4 v[8:9], v[4:7], off
	v_lshlrev_b32_e32 v8, 16, v0
	v_and_b32_e32 v9, 0xffff0000, v0
	v_or_b32_e32 v5, s5, v111
	v_lshlrev_b32_e32 v5, 2, v5
	v_or_b32_e32 v4, s43, v121
	v_ashrrev_i32_e32 v5, 31, v4
	v_lshlrev_b64 v[4:5], 12, v[4:5]
	v_lshl_add_u64 v[4:5], v[116:117], 0, v[4:5]
	v_pk_add_f32 v[10:11], v[36:37], v[210:211] op_sel_hi:[1,0]
	s_nop 0
	v_pk_mul_f32 v[8:9], v[10:11], v[8:9]
	v_pk_add_f32 v[10:11], v[38:39], v[210:211] op_sel_hi:[1,0]
	v_cvt_pk_bf16_f32 v0, v8, v9
	v_lshlrev_b32_e32 v8, 16, v1
	v_and_b32_e32 v9, 0xffff0000, v1
	v_pk_mul_f32 v[8:9], v[10:11], v[8:9]
	v_pk_add_f32 v[10:11], v[32:33], v[210:211] op_sel_hi:[1,0]
	v_cvt_pk_bf16_f32 v1, v8, v9
	v_lshlrev_b32_e32 v8, 16, v2
	v_and_b32_e32 v9, 0xffff0000, v2
	v_pk_mul_f32 v[8:9], v[10:11], v[8:9]
	v_pk_add_f32 v[6:7], v[34:35], v[210:211] op_sel_hi:[1,0]
	v_cvt_pk_bf16_f32 v2, v8, v9
	v_lshlrev_b32_e32 v8, 16, v3
	v_and_b32_e32 v9, 0xffff0000, v3
	v_pk_mul_f32 v[6:7], v[6:7], v[8:9]
	s_nop 0
	v_cvt_pk_bf16_f32 v3, v6, v7
	global_store_dwordx4 v[4:5], v[0:3], off
	s_barrier
	s_cbranch_scc1 .LBB0_725
